# ml3 phase: redundant clamped pair-items of the partial last round skipped (on top of coarse-attention / conversion skips and scan remainder placement)
# speedup vs baseline: 1.0069x; 1.0038x over previous
; DI void ml3_pair(const Params& p, int layer, int it2, int cpc, int n5, int last, char* smem) {
;     const int tid = otid(), lane = tid & 63, wave = tid >> 6, pr = wave >> 1, jw = wave & 1, r = lane & 31, h = lane >> 5, t2 = tid & 127;
;     int idx = 2 * it2 + pr; if (idx >= n5) idx = n5 - 1;
;     const int item = (idx / cpc) * NCH + (last ? 4 : 0) + idx % cpc;
;     const int c = item % NCH, head = (item / NCH) & 3, b = item / (NCH * 4);
;     const size_t row0 = seq_row(b, c);
;     char* slot = smem + pr * 36864;
;     bf16_t* sKb = (bf16_t*)slot;
;     bf16_t* sVt = sKb + 64 * 72;
;     bf16_t* sC = sVt + 64 * 68;
;     float* sg = (float*)(sC + 64 * 72);
;     float* sn = sg + 256;
;     {
;         u32x4 kq[4], vq[4];
; #pragma unroll
;         for (int i = 0; i < 4; ++i) {
;             const int cc = t2 + 128 * i, row = cc >> 3, c8 = (cc & 7) * 8;
;             const bf16_t* src = p.ACT + (row0 + row) * PW + head * 64 + c8;
;             kq[i] = *(const u32x4*)(src + 1280); vq[i] = *(const u32x4*)(src + 1536);
;         }
;         __builtin_amdgcn_sched_barrier(0);
; #pragma unroll
;         for (int i = 0; i < 4; ++i) {
;             const int cc = t2 + 128 * i, row = cc >> 3, c8 = (cc & 7) * 8;
;             *(u32x4*)(sKb + row * 72 + c8) = kq[i];
;             const u32x4 vv = vq[i];
;             sVt[(c8 + 0) * 68 + row] = (bf16_t)(vv.x & 0xffffu); sVt[(c8 + 1) * 68 + row] = (bf16_t)(vv.x >> 16);
;             sVt[(c8 + 2) * 68 + row] = (bf16_t)(vv.y & 0xffffu); sVt[(c8 + 3) * 68 + row] = (bf16_t)(vv.y >> 16);
;             sVt[(c8 + 4) * 68 + row] = (bf16_t)(vv.z & 0xffffu); sVt[(c8 + 5) * 68 + row] = (bf16_t)(vv.z >> 16);
;             sVt[(c8 + 6) * 68 + row] = (bf16_t)(vv.w & 0xffffu); sVt[(c8 + 7) * 68 + row] = (bf16_t)(vv.w >> 16);
;         }
;     }
;     const size_t chf = ((size_t)(b * 4 + head) * 2 + 0) * NCH + chain_pos(0, c), chb = ((size_t)(b * 4 + head) * 2 + 1) * NCH + chain_pos(1, c);
;     if (jw == 0) {
;         const float* gp = p.GATES + (row0 + lane) * 16 + head;
;         const float lif = gp[0], lff = log_sigmoid(gp[4]), lib = gp[8], lfb = log_sigmoid(gp[12]);
;         float vf = lff, vb = lfb;
; #pragma unroll
;         for (int o = 1; o < 64; o <<= 1) {
;             const float tf = shl(vf, lane - o), tb = shl(vb, lane + o);
;             if (lane >= o) vf += tf;
;             if (lane + o < 64) vb += tb;
.LBB0_53:
	v_readlane_b32 s0, v253, 5
	s_mul_i32 s0, s2, s0
	v_readlane_b32 s1, v253, 2
	s_add_i32 s0, s0, s1
	v_readlane_b32 s1, v254, 22
	v_mov_b32_e32 v8, v228
	s_cmp_gt_i32 s0, s1
	s_cbranch_scc1 .LBB0_127
	s_movk_i32 s1, 0x84
	v_ashrrev_i32_e32 v5, 7, v8
	v_lshl_add_u32 v0, s0, 1, v5
	v_readlane_b32 s0, v254, 18
	s_mov_b32 s51, s2
	s_mov_b32 s50, s20
	v_min_i32_e32 v0, s0, v0
	v_sub_u32_e32 v2, 0, v0
	v_max_i32_e32 v2, v0, v2
	v_mul_hi_u32 v3, v2, v126
	v_mul_lo_u32 v4, v3, s20
	v_sub_u32_e32 v2, v2, v4
	v_add_u32_e32 v4, 1, v3
	v_cmp_le_u32_e32 vcc, s20, v2
	v_ashrrev_i32_e32 v1, 31, v0
	v_readlane_b32 s0, v254, 19
	v_cndmask_b32_e32 v3, v3, v4, vcc
	v_subrev_u32_e32 v4, s20, v2
	v_cndmask_b32_e32 v2, v2, v4, vcc
	v_add_u32_e32 v4, 1, v3
	v_cmp_le_u32_e32 vcc, s20, v2
	s_nop 1
	v_cndmask_b32_e32 v2, v3, v4, vcc
	v_xor_b32_e32 v2, v2, v1
	v_sub_u32_e32 v1, v2, v1
	v_mul_lo_u32 v2, v1, s1
	v_mul_lo_u32 v1, v1, s20
	v_sub_u32_e32 v0, v0, v1
	v_add3_u32 v1, v2, s0, v0
	s_mov_b32 s0, 0x3e0f83e1
	v_mul_hi_i32 v2, v1, s0
	v_ashrrev_i32_e32 v0, 5, v2
	v_lshrrev_b32_e32 v3, 31, v2
	v_add_u32_e32 v0, v0, v3
	v_mul_lo_u32 v4, v0, s1
	v_sub_u32_e32 v4, v1, v4
	v_ashrrev_i32_e32 v1, 7, v2
	v_add_u32_e32 v6, v1, v3
	v_cmp_lt_i32_e32 vcc, 3, v4
	s_and_saveexec_b64 s[0:1], vcc
	s_xor_b64 s[0:1], exec, s[0:1]
	v_ashrrev_i32_e32 v7, 31, v6
	v_mov_b32_e32 v1, 0xffffff00
	v_lshlrev_b64 v[2:3], 13, v[6:7]
	v_lshl_add_u32 v160, v4, 6, v1
	v_lshl_add_u64 v[2:3], v[2:3], 0, v[160:161]
	s_or_saveexec_b64 s[0:1], s[0:1]
	v_mov_b32_e32 v9, 0x87
	s_xor_b64 exec, exec, s[0:1]
	v_mov_b32_e32 v1, 0x10000
	v_lshl_add_u32 v2, v6, 8, v1
	v_lshlrev_b32_e32 v10, 6, v4
	v_ashrrev_i32_e32 v3, 31, v2
	v_ashrrev_i32_e32 v11, 31, v10
	v_lshl_add_u64 v[2:3], v[2:3], 0, v[10:11]
	v_mov_b32_e32 v9, 3
	s_or_b64 exec, exec, s[0:1]
	v_and_b32_e32 v7, 3, v0
	v_lshlrev_b32_e32 v0, 3, v8
	v_and_b32_e32 v44, 56, v0
	v_lshlrev_b32_e32 v0, 7, v7
	v_mov_b32_e32 v1, v161
	v_lshl_add_u64 v[10:11], s[64:65], 0, v[0:1]
	v_lshlrev_b32_e32 v0, 1, v44
	s_waitcnt vmcnt(26)
	v_bfe_u32 v42, v8, 3, 4
	v_mov_b32_e32 v43, v161
	v_lshl_add_u64 v[10:11], v[10:11], 0, v[0:1]
	v_lshl_add_u64 v[12:13], v[2:3], 0, v[42:43]
	s_movk_i32 s2, 0x1400
	v_mad_u64_u32 v[14:15], s[0:1], v12, s2, v[10:11]
	v_mov_b32_e32 v12, v15
	v_mad_u64_u32 v[12:13], s[0:1], v13, s2, v[12:13]
	v_mov_b32_e32 v15, v12
	v_or_b32_e32 v12, 16, v42
	v_mov_b32_e32 v13, v161
	v_lshl_add_u64 v[12:13], v[2:3], 0, v[12:13]
	s_waitcnt vmcnt(16)
	v_mad_u64_u32 v[22:23], s[0:1], v12, s2, v[10:11]
	v_mov_b32_e32 v12, v23
	v_mad_u64_u32 v[12:13], s[0:1], v13, s2, v[12:13]
	v_mov_b32_e32 v23, v12
	v_or_b32_e32 v12, 32, v42
	v_mov_b32_e32 v13, v161
	v_lshl_add_u64 v[12:13], v[2:3], 0, v[12:13]
	v_mad_u64_u32 v[30:31], s[0:1], v12, s2, v[10:11]
	v_mov_b32_e32 v12, v31
	v_mad_u64_u32 v[12:13], s[0:1], v13, s2, v[12:13]
	v_mov_b32_e32 v31, v12
	v_or_b32_e32 v12, 48, v42
	v_mov_b32_e32 v13, v161
	v_lshl_add_u64 v[12:13], v[2:3], 0, v[12:13]
	v_mad_u64_u32 v[38:39], s[0:1], v12, s2, v[10:11]
	v_mov_b32_e32 v10, v39
	v_mad_u64_u32 v[10:11], s[0:1], v13, s2, v[10:11]
	v_mov_b32_e32 v39, v10
	global_load_dwordx4 v[10:13], v[14:15], off offset:2560
	s_nop 0
	global_load_dwordx4 v[14:17], v[14:15], off offset:3072
	s_nop 0
	global_load_dwordx4 v[18:21], v[22:23], off offset:2560
	s_nop 0
	global_load_dwordx4 v[22:25], v[22:23], off offset:3072
	s_nop 0
	global_load_dwordx4 v[26:29], v[30:31], off offset:2560
	s_nop 0
	global_load_dwordx4 v[30:33], v[30:31], off offset:3072
	s_nop 0
	global_load_dwordx4 v[34:37], v[38:39], off offset:2560
	s_nop 0
	global_load_dwordx4 v[38:41], v[38:39], off offset:3072
	v_mul_lo_u32 v1, v5, s96
	v_and_b32_e32 v160, 63, v8
	v_add_u32_e32 v127, s25, v1
	v_mul_u32_u24_e32 v5, 0x48, v42
	v_mul_u32_u24_e32 v1, 0x44, v44
	v_lshlrev_b32_e32 v5, 1, v5
	v_add3_u32 v128, v127, v0, v5
	v_lshlrev_b32_e32 v5, 1, v42
	v_lshlrev_b32_e32 v1, 1, v1
	v_add3_u32 v1, v127, v5, v1
	s_waitcnt vmcnt(7)
	ds_write_b128 v128, v[10:13]
	s_waitcnt vmcnt(6)
	ds_write_b16 v1, v14 offset:9216
	ds_write_b16_d16_hi v1, v14 offset:9352
	ds_write_b16 v1, v15 offset:9488
	ds_write_b16_d16_hi v1, v15 offset:9624
	ds_write_b16 v1, v16 offset:9760
	ds_write_b16_d16_hi v1, v16 offset:9896
	ds_write_b16 v1, v17 offset:10032
	ds_write_b16_d16_hi v1, v17 offset:10168
	s_waitcnt vmcnt(5)
	ds_write_b128 v128, v[18:21] offset:2304
	s_waitcnt vmcnt(4)
	ds_write_b16 v1, v22 offset:9248
	ds_write_b16_d16_hi v1, v22 offset:9384
	ds_write_b16 v1, v23 offset:9520
	ds_write_b16_d16_hi v1, v23 offset:9656
	ds_write_b16 v1, v24 offset:9792
	ds_write_b16_d16_hi v1, v24 offset:9928
	ds_write_b16 v1, v25 offset:10064
	ds_write_b16_d16_hi v1, v25 offset:10200
	s_waitcnt vmcnt(3)
	ds_write_b128 v128, v[26:29] offset:4608
	s_waitcnt vmcnt(2)
	ds_write_b16 v1, v30 offset:9280
	ds_write_b16_d16_hi v1, v30 offset:9416
	ds_write_b16 v1, v31 offset:9552
	ds_write_b16_d16_hi v1, v31 offset:9688
	ds_write_b16 v1, v32 offset:9824
	ds_write_b16_d16_hi v1, v32 offset:9960
	ds_write_b16 v1, v33 offset:10096
	ds_write_b16_d16_hi v1, v33 offset:10232
	s_waitcnt vmcnt(1)
	ds_write_b128 v128, v[34:37] offset:6912
	s_waitcnt vmcnt(0)
	ds_write_b16 v1, v38 offset:9312
	ds_write_b16_d16_hi v1, v38 offset:9448
	ds_write_b16 v1, v39 offset:9584
	ds_write_b16_d16_hi v1, v39 offset:9720
	ds_write_b16 v1, v40 offset:9856
	ds_write_b16_d16_hi v1, v40 offset:9992
	ds_write_b16 v1, v41 offset:10128
	ds_write_b16_d16_hi v1, v41 offset:10264
	v_lshl_or_b32 v1, v6, 2, v7
	v_ashrrev_i32_e32 v5, 31, v4
	s_movk_i32 s4, 0x108
	v_mad_i64_i32 v[92:93], s[0:1], v1, s4, v[4:5]
	v_sub_u32_e32 v4, v9, v4
	v_mov_b32_e32 v5, v161
	v_mad_i64_i32 v[4:5], s[0:1], v1, s4, v[4:5]
	s_mov_b64 s[0:1], 0x84
	v_and_b32_e32 v1, 64, v8
	v_lshl_add_u64 v[94:95], v[4:5], 0, s[0:1]
	v_cmp_ne_u32_e32 vcc, 0, v1
	v_lshlrev_b32_e32 v1, 2, v160
	s_and_saveexec_b64 s[0:1], vcc
	s_xor_b64 s[0:1], exec, s[0:1]
	s_cbranch_execz .LBB0_59
	v_mov_b64_e32 v[4:5], s[68:69]
	s_movk_i32 s6, 0x2080
	v_mad_u64_u32 v[10:11], s[4:5], v92, s6, v[4:5]
	v_mov_b32_e32 v6, v11
	v_mad_u64_u32 v[12:13], s[4:5], v93, s6, v[6:7]
	v_mov_b32_e32 v11, v12
	v_lshlrev_b32_e32 v12, 1, v160
	v_mov_b32_e32 v13, v161
	v_lshl_add_u64 v[10:11], v[10:11], 0, v[12:13]
	v_add_co_u32_e32 v10, vcc, 0x2000, v10
	v_mad_u64_u32 v[4:5], s[4:5], v94, s6, v[4:5]
	s_nop 0
	v_addc_co_u32_e32 v11, vcc, 0, v11, vcc
	v_mov_b32_e32 v6, v5
	global_load_ushort v1, v[10:11], off
	v_mad_u64_u32 v[10:11], s[4:5], v95, s6, v[6:7]
	v_mov_b32_e32 v5, v10
	v_lshl_add_u64 v[4:5], v[4:5], 0, v[12:13]
	v_add_co_u32_e32 v4, vcc, 0x2000, v4
	s_waitcnt vmcnt(0)
	v_lshlrev_b32_e32 v9, 16, v1
	v_addc_co_u32_e32 v5, vcc, 0, v5, vcc
	global_load_ushort v4, v[4:5], off
	v_lshlrev_b32_e32 v1, 2, v160
	v_add_u32_e32 v14, v127, v1
	s_waitcnt vmcnt(0)
	v_lshlrev_b32_e32 v4, 16, v4
	ds_write2st64_b32 v14, v9, v4 offset0:110 offset1:111
